# nt cache hints on the read-once residual loads (P7 x, P10 x_new) and the final output stores of the FFN-down epilogue
# baseline (speedup 1.0000x reference)
; #define EPI_FENCE() asm volatile("" ::: "memory")
;     __device__ __forceinline__ void operator()(const Acc& acc, const Unit& u, int wr, int wc, int fr, int fq) const {
;         const int row0 = u.pm * BM + wr * 64 + fr, col0 = u.pn * BM + wc * 32 + 8 * fq;
;         const float* gp = gate + (size_t)(u.pm >> 4) * ADAW + col0;
;         f32x4 gv[2][2];
; #pragma unroll
;         for (int bj = 0; bj < 2; ++bj) { gv[bj][0] = *(const f32x4*)(gp + bj * HALF); gv[bj][1] = *(const f32x4*)(gp + bj * HALF + 4); }
; #pragma unroll
;         for (int ai = 0; ai < 2; ++ai)
; #pragma unroll
;             for (int m = 0; m < 4; ++m) { const size_t off = (size_t)(row0 + ai * HALF + m * 16) * DM + col0;
; #pragma unroll
;                 for (int bj = 0; bj < 2; ++bj) {
;                     const f32x4 b0 = *(const f32x4*)(base + off + bj * HALF), b1 = *(const f32x4*)(base + off + bj * HALF + 4);
;                     *(f32x4*)(out + off + bj * HALF) = b0 + gv[bj][0] * acc[ai][bj][m][0];
;                     *(f32x4*)(out + off + bj * HALF + 4) = b1 + gv[bj][1] * acc[ai][bj][m][1]; }
;                 EPI_FENCE(); }
.LBB0_825:
	v_lshl_add_u32 v184, s44, 8, v168
	v_lshl_or_b32 v182, s60, 8, v170
	s_ashr_i32 s0, s44, 4
	v_ashrrev_i32_e32 v185, 31, v184
	s_mul_hi_i32 s1, s0, 0xc000
	s_mul_i32 s0, s0, 0xc000
	v_ashrrev_i32_e32 v183, 31, v182
	v_lshlrev_b64 v[128:129], 11, v[184:185]
	s_add_u32 s0, s53, s0
	v_lshl_add_u64 v[128:129], v[128:129], 0, v[182:183]
	s_addc_u32 s1, s54, s1
	v_lshlrev_b64 v[160:161], 2, v[128:129]
	v_lshl_add_u64 v[132:133], v[182:183], 2, s[0:1]
	v_lshl_add_u64 v[186:187], s[36:37], 0, v[160:161]
	v_lshl_add_u64 v[188:189], s[68:69], 0, v[160:161]
	s_andn2_b64 vcc, exec, s[2:3]
	s_mov_b64 s[0:1], -1
	global_load_dwordx4 v[140:143], v[132:133], off
	global_load_dwordx4 v[136:139], v[132:133], off offset:16
	global_load_dwordx4 v[128:131], v[132:133], off offset:528
	global_load_dwordx4 v[132:135], v[132:133], off offset:512
	s_mov_b32 s99, 0
	global_load_dwordx4 v[190:193], v[186:187], off nt
	global_load_dwordx4 v[194:197], v[186:187], off offset:16 nt
	global_load_dwordx4 v[198:201], v[186:187], off offset:512 nt
	global_load_dwordx4 v[202:205], v[186:187], off offset:528 nt
	s_mov_b32 s98, 0x20000
	v_lshl_add_u64 v[186:187], v[186:187], 0, s[98:99]
	global_load_dwordx4 v[206:209], v[186:187], off nt
	global_load_dwordx4 v[210:213], v[186:187], off offset:16 nt
	global_load_dwordx4 v[214:217], v[186:187], off offset:512 nt
	global_load_dwordx4 v[220:223], v[186:187], off offset:528 nt
	s_mov_b32 s98, 0x20000
	v_lshl_add_u64 v[186:187], v[186:187], 0, s[98:99]
	s_waitcnt vmcnt(4)
	v_pk_fma_f32 v[126:127], v[126:127], v[142:143], v[192:193]
	v_pk_fma_f32 v[124:125], v[124:125], v[140:141], v[190:191]
	v_pk_fma_f32 v[122:123], v[122:123], v[138:139], v[196:197]
	v_pk_fma_f32 v[120:121], v[120:121], v[136:137], v[194:195]
	v_pk_fma_f32 v[114:115], v[114:115], v[134:135], v[200:201]
	v_pk_fma_f32 v[112:113], v[112:113], v[132:133], v[198:199]
	v_pk_fma_f32 v[110:111], v[110:111], v[130:131], v[204:205]
	v_pk_fma_f32 v[108:109], v[108:109], v[128:129], v[202:203]
	global_store_dwordx4 v[188:189], v[124:127], off
	global_store_dwordx4 v[188:189], v[120:123], off offset:16
	global_store_dwordx4 v[188:189], v[112:115], off offset:512
	global_store_dwordx4 v[188:189], v[108:111], off offset:528
	s_mov_b32 s98, 0x20000
	v_lshl_add_u64 v[188:189], v[188:189], 0, s[98:99]
	global_load_dwordx4 v[190:193], v[186:187], off nt
	global_load_dwordx4 v[194:197], v[186:187], off offset:16 nt
	global_load_dwordx4 v[198:201], v[186:187], off offset:512 nt
	global_load_dwordx4 v[202:205], v[186:187], off offset:528 nt
	s_mov_b32 s98, 0x20000
	v_lshl_add_u64 v[186:187], v[186:187], 0, s[98:99]
	s_waitcnt vmcnt(8)
	v_pk_fma_f32 v[118:119], v[118:119], v[142:143], v[208:209]
	v_pk_fma_f32 v[116:117], v[116:117], v[140:141], v[206:207]
	v_pk_fma_f32 v[106:107], v[106:107], v[138:139], v[212:213]
	v_pk_fma_f32 v[104:105], v[104:105], v[136:137], v[210:211]
	v_pk_fma_f32 v[98:99], v[98:99], v[134:135], v[216:217]
	v_pk_fma_f32 v[96:97], v[96:97], v[132:133], v[214:215]
	v_pk_fma_f32 v[94:95], v[94:95], v[130:131], v[222:223]
	v_pk_fma_f32 v[92:93], v[92:93], v[128:129], v[220:221]
	global_store_dwordx4 v[188:189], v[116:119], off
	global_store_dwordx4 v[188:189], v[104:107], off offset:16
	global_store_dwordx4 v[188:189], v[96:99], off offset:512
	global_store_dwordx4 v[188:189], v[92:95], off offset:528
	s_mov_b32 s98, 0x20000
	v_lshl_add_u64 v[188:189], v[188:189], 0, s[98:99]
	global_load_dwordx4 v[206:209], v[186:187], off nt
	global_load_dwordx4 v[210:213], v[186:187], off offset:16 nt
	global_load_dwordx4 v[214:217], v[186:187], off offset:512 nt
	global_load_dwordx4 v[220:223], v[186:187], off offset:528 nt
	s_mov_b32 s98, 0xa0000
	v_lshl_add_u64 v[186:187], v[186:187], 0, s[98:99]
	s_waitcnt vmcnt(8)
	v_pk_fma_f32 v[102:103], v[102:103], v[142:143], v[192:193]
	v_pk_fma_f32 v[100:101], v[100:101], v[140:141], v[190:191]
	v_pk_fma_f32 v[90:91], v[90:91], v[138:139], v[196:197]
	v_pk_fma_f32 v[88:89], v[88:89], v[136:137], v[194:195]
	v_pk_fma_f32 v[82:83], v[82:83], v[134:135], v[200:201]
	v_pk_fma_f32 v[80:81], v[80:81], v[132:133], v[198:199]
	v_pk_fma_f32 v[78:79], v[78:79], v[130:131], v[204:205]
	v_pk_fma_f32 v[76:77], v[76:77], v[128:129], v[202:203]
	global_store_dwordx4 v[188:189], v[100:103], off
	global_store_dwordx4 v[188:189], v[88:91], off offset:16
	global_store_dwordx4 v[188:189], v[80:83], off offset:512
	global_store_dwordx4 v[188:189], v[76:79], off offset:528
	s_mov_b32 s98, 0x20000
	v_lshl_add_u64 v[188:189], v[188:189], 0, s[98:99]
	global_load_dwordx4 v[190:193], v[186:187], off nt
	global_load_dwordx4 v[194:197], v[186:187], off offset:16 nt
	global_load_dwordx4 v[198:201], v[186:187], off offset:512 nt
	global_load_dwordx4 v[202:205], v[186:187], off offset:528 nt
	s_mov_b32 s98, 0x20000
	v_lshl_add_u64 v[186:187], v[186:187], 0, s[98:99]
	s_waitcnt vmcnt(8)
; #define EPI_FENCE() asm volatile("" ::: "memory")
;     __device__ __forceinline__ void operator()(const Acc& acc, const Unit& u, int wr, int wc, int fr, int fq) const {
;     ...
;             for (int m = 0; m < 4; ++m) { const size_t off = (size_t)(row0 + ai * HALF + m * 16) * DM + col0;
; #pragma unroll
;                 for (int bj = 0; bj < 2; ++bj) {
;                     const f32x4 b0 = *(const f32x4*)(base + off + bj * HALF), b1 = *(const f32x4*)(base + off + bj * HALF + 4);
;                     *(f32x4*)(out + off + bj * HALF) = b0 + gv[bj][0] * acc[ai][bj][m][0];
;                     *(f32x4*)(out + off + bj * HALF + 4) = b1 + gv[bj][1] * acc[ai][bj][m][1]; }
;                 EPI_FENCE(); }
	v_pk_fma_f32 v[86:87], v[86:87], v[142:143], v[208:209]
	v_pk_fma_f32 v[84:85], v[84:85], v[140:141], v[206:207]
	v_pk_fma_f32 v[74:75], v[74:75], v[138:139], v[212:213]
	v_pk_fma_f32 v[72:73], v[72:73], v[136:137], v[210:211]
	v_pk_fma_f32 v[70:71], v[70:71], v[134:135], v[216:217]
	v_pk_fma_f32 v[68:69], v[68:69], v[132:133], v[214:215]
	v_pk_fma_f32 v[66:67], v[66:67], v[130:131], v[222:223]
	v_pk_fma_f32 v[64:65], v[64:65], v[128:129], v[220:221]
	global_store_dwordx4 v[188:189], v[84:87], off
	global_store_dwordx4 v[188:189], v[72:75], off offset:16
	global_store_dwordx4 v[188:189], v[68:71], off offset:512
	global_store_dwordx4 v[188:189], v[64:67], off offset:528
	s_mov_b32 s98, 0xa0000
	v_lshl_add_u64 v[188:189], v[188:189], 0, s[98:99]
	global_load_dwordx4 v[206:209], v[186:187], off nt
	global_load_dwordx4 v[210:213], v[186:187], off offset:16 nt
	global_load_dwordx4 v[214:217], v[186:187], off offset:512 nt
	global_load_dwordx4 v[220:223], v[186:187], off offset:528 nt
	s_mov_b32 s98, 0x20000
	v_lshl_add_u64 v[186:187], v[186:187], 0, s[98:99]
	s_waitcnt vmcnt(8)
	v_pk_fma_f32 v[62:63], v[62:63], v[142:143], v[192:193]
	v_pk_fma_f32 v[60:61], v[60:61], v[140:141], v[190:191]
	v_pk_fma_f32 v[58:59], v[58:59], v[138:139], v[196:197]
	v_pk_fma_f32 v[56:57], v[56:57], v[136:137], v[194:195]
	v_pk_fma_f32 v[50:51], v[50:51], v[134:135], v[200:201]
	v_pk_fma_f32 v[48:49], v[48:49], v[132:133], v[198:199]
	v_pk_fma_f32 v[46:47], v[46:47], v[130:131], v[204:205]
	v_pk_fma_f32 v[44:45], v[44:45], v[128:129], v[202:203]
	global_store_dwordx4 v[188:189], v[60:63], off
	global_store_dwordx4 v[188:189], v[56:59], off offset:16
	global_store_dwordx4 v[188:189], v[48:51], off offset:512
	global_store_dwordx4 v[188:189], v[44:47], off offset:528
	s_mov_b32 s98, 0x20000
	v_lshl_add_u64 v[188:189], v[188:189], 0, s[98:99]
	global_load_dwordx4 v[190:193], v[186:187], off nt
	global_load_dwordx4 v[194:197], v[186:187], off offset:16 nt
	global_load_dwordx4 v[198:201], v[186:187], off offset:512 nt
	global_load_dwordx4 v[202:205], v[186:187], off offset:528 nt
	s_mov_b32 s98, 0x20000
	v_lshl_add_u64 v[186:187], v[186:187], 0, s[98:99]
	s_waitcnt vmcnt(8)
	v_pk_fma_f32 v[54:55], v[54:55], v[142:143], v[208:209]
	v_pk_fma_f32 v[52:53], v[52:53], v[140:141], v[206:207]
	v_pk_fma_f32 v[42:43], v[42:43], v[138:139], v[212:213]
	v_pk_fma_f32 v[40:41], v[40:41], v[136:137], v[210:211]
	v_pk_fma_f32 v[34:35], v[34:35], v[134:135], v[216:217]
	v_pk_fma_f32 v[32:33], v[32:33], v[132:133], v[214:215]
	v_pk_fma_f32 v[30:31], v[30:31], v[130:131], v[222:223]
	v_pk_fma_f32 v[28:29], v[28:29], v[128:129], v[220:221]
	global_store_dwordx4 v[188:189], v[52:55], off
	global_store_dwordx4 v[188:189], v[40:43], off offset:16
	global_store_dwordx4 v[188:189], v[32:35], off offset:512
	global_store_dwordx4 v[188:189], v[28:31], off offset:528
	s_mov_b32 s98, 0x20000
	v_lshl_add_u64 v[188:189], v[188:189], 0, s[98:99]
	global_load_dwordx4 v[206:209], v[186:187], off nt
	global_load_dwordx4 v[210:213], v[186:187], off offset:16 nt
	global_load_dwordx4 v[214:217], v[186:187], off offset:512 nt
	global_load_dwordx4 v[220:223], v[186:187], off offset:528 nt
	s_waitcnt vmcnt(8)
	v_pk_fma_f32 v[38:39], v[38:39], v[142:143], v[192:193]
	v_pk_fma_f32 v[36:37], v[36:37], v[140:141], v[190:191]
	v_pk_fma_f32 v[26:27], v[26:27], v[138:139], v[196:197]
	v_pk_fma_f32 v[24:25], v[24:25], v[136:137], v[194:195]
	v_pk_fma_f32 v[18:19], v[18:19], v[134:135], v[200:201]
	v_pk_fma_f32 v[16:17], v[16:17], v[132:133], v[198:199]
	v_pk_fma_f32 v[14:15], v[14:15], v[130:131], v[204:205]
	v_pk_fma_f32 v[12:13], v[12:13], v[128:129], v[202:203]
	global_store_dwordx4 v[188:189], v[36:39], off
	global_store_dwordx4 v[188:189], v[24:27], off offset:16
	global_store_dwordx4 v[188:189], v[16:19], off offset:512
	global_store_dwordx4 v[188:189], v[12:15], off offset:528
	s_mov_b32 s98, 0x20000
	v_lshl_add_u64 v[188:189], v[188:189], 0, s[98:99]
	s_waitcnt vmcnt(4)
	v_pk_fma_f32 v[22:23], v[22:23], v[142:143], v[208:209]
	v_pk_fma_f32 v[20:21], v[20:21], v[140:141], v[206:207]
	v_pk_fma_f32 v[10:11], v[10:11], v[138:139], v[212:213]
	v_pk_fma_f32 v[8:9], v[8:9], v[136:137], v[210:211]
	v_pk_fma_f32 v[6:7], v[6:7], v[134:135], v[216:217]
	v_pk_fma_f32 v[4:5], v[4:5], v[132:133], v[214:215]
	v_pk_fma_f32 v[2:3], v[2:3], v[130:131], v[222:223]
	v_pk_fma_f32 v[0:1], v[0:1], v[128:129], v[220:221]
	global_store_dwordx4 v[188:189], v[20:23], off
	global_store_dwordx4 v[188:189], v[8:11], off offset:16
	global_store_dwordx4 v[188:189], v[4:7], off offset:512
	global_store_dwordx4 v[188:189], v[0:3], off offset:528
	s_cbranch_vccnz .LBB0_814
	s_andn2_b64 vcc, exec, s[6:7]
	s_cbranch_vccnz .LBB0_813
	s_barrier
	s_branch .LBB0_813

; #define EPI_FENCE() asm volatile("" ::: "memory")
;     __device__ __forceinline__ void operator()(const Acc& acc, const Unit& u, int wr, int wc, int fr, int fq) const {
;         const int row0 = u.pm * BM + wr * 64 + fr, col0 = u.pn * BM + wc * 32 + 8 * fq;
;         const float* gp = gate + (size_t)(u.pm >> 4) * ADAW + col0;
;         f32x4 gv[2][2];
; #pragma unroll
;         for (int bj = 0; bj < 2; ++bj) { gv[bj][0] = *(const f32x4*)(gp + bj * HALF); gv[bj][1] = *(const f32x4*)(gp + bj * HALF + 4); }
; #pragma unroll
;         for (int ai = 0; ai < 2; ++ai)
; #pragma unroll
;             for (int m = 0; m < 4; ++m) { const size_t off = (size_t)(row0 + ai * HALF + m * 16) * DM + col0;
; #pragma unroll
;                 for (int bj = 0; bj < 2; ++bj) {
;                     const f32x4 b0 = *(const f32x4*)(base + off + bj * HALF), b1 = *(const f32x4*)(base + off + bj * HALF + 4);
;                     *(f32x4*)(out + off + bj * HALF) = b0 + gv[bj][0] * acc[ai][bj][m][0];
;                     *(f32x4*)(out + off + bj * HALF + 4) = b1 + gv[bj][1] * acc[ai][bj][m][1]; }
;                 EPI_FENCE(); }
.LBB0_1051:
	v_lshl_or_b32 v128, s52, 8, v164
	s_ashr_i32 s24, s51, 4
	v_lshl_add_u32 v186, s51, 8, v162
	s_mul_hi_i32 s25, s24, 0xc000
	s_mul_i32 s24, s24, 0xc000
	v_ashrrev_i32_e32 v129, 31, v128
	v_ashrrev_i32_e32 v187, 31, v186
	s_add_u32 s24, s38, s24
	v_lshlrev_b64 v[184:185], 2, v[128:129]
	v_lshlrev_b64 v[128:129], 13, v[186:187]
	s_addc_u32 s25, s39, s25
	v_lshl_add_u64 v[128:129], s[68:69], 0, v[128:129]
	v_lshl_add_u64 v[136:137], s[24:25], 0, v[184:185]
	v_lshl_add_u64 v[160:161], v[128:129], 0, v[184:185]
	global_load_dwordx4 v[132:135], v[136:137], off
	global_load_dwordx4 v[128:131], v[136:137], off offset:16
	global_load_dwordx4 v[140:143], v[136:137], off offset:512
	global_load_dwordx4 v[136:139], v[136:137], off offset:528
	v_mov_b32_e32 v188, v160
	v_mov_b32_e32 v189, v161
	s_mov_b32 s99, 0
	global_load_dwordx4 v[168:171], v[160:161], off nt
	global_load_dwordx4 v[172:175], v[160:161], off offset:16 nt
	global_load_dwordx4 v[176:179], v[160:161], off offset:512 nt
	global_load_dwordx4 v[180:183], v[160:161], off offset:528 nt
	s_mov_b32 s98, 0x20000
	v_lshl_add_u64 v[160:161], v[160:161], 0, s[98:99]
	global_load_dwordx4 v[192:195], v[160:161], off nt
	global_load_dwordx4 v[196:199], v[160:161], off offset:16 nt
	global_load_dwordx4 v[200:203], v[160:161], off offset:512 nt
	global_load_dwordx4 v[204:207], v[160:161], off offset:528 nt
	s_mov_b32 s98, 0x20000
	v_lshl_add_u64 v[160:161], v[160:161], 0, s[98:99]
	s_waitcnt vmcnt(4)
	v_pk_fma_f32 v[126:127], v[126:127], v[134:135], v[170:171]
	v_pk_fma_f32 v[124:125], v[124:125], v[132:133], v[168:169]
	v_pk_fma_f32 v[122:123], v[122:123], v[130:131], v[174:175]
	v_pk_fma_f32 v[120:121], v[120:121], v[128:129], v[172:173]
	v_pk_fma_f32 v[118:119], v[118:119], v[142:143], v[178:179]
	v_pk_fma_f32 v[116:117], v[116:117], v[140:141], v[176:177]
	v_pk_fma_f32 v[114:115], v[114:115], v[138:139], v[182:183]
	v_pk_fma_f32 v[112:113], v[112:113], v[136:137], v[180:181]
	global_store_dwordx4 v[188:189], v[124:127], off nt
	global_store_dwordx4 v[188:189], v[120:123], off offset:16 nt
	global_store_dwordx4 v[188:189], v[116:119], off offset:512 nt
	global_store_dwordx4 v[188:189], v[112:115], off offset:528 nt
	s_mov_b32 s98, 0x20000
	v_lshl_add_u64 v[188:189], v[188:189], 0, s[98:99]
	global_load_dwordx4 v[168:171], v[160:161], off nt
	global_load_dwordx4 v[172:175], v[160:161], off offset:16 nt
	global_load_dwordx4 v[176:179], v[160:161], off offset:512 nt
	global_load_dwordx4 v[180:183], v[160:161], off offset:528 nt
	s_mov_b32 s98, 0x20000
	v_lshl_add_u64 v[160:161], v[160:161], 0, s[98:99]
	s_waitcnt vmcnt(8)
	v_pk_fma_f32 v[110:111], v[110:111], v[134:135], v[194:195]
	v_pk_fma_f32 v[108:109], v[108:109], v[132:133], v[192:193]
	v_pk_fma_f32 v[106:107], v[106:107], v[130:131], v[198:199]
	v_pk_fma_f32 v[104:105], v[104:105], v[128:129], v[196:197]
	v_pk_fma_f32 v[102:103], v[102:103], v[142:143], v[202:203]
	v_pk_fma_f32 v[100:101], v[100:101], v[140:141], v[200:201]
	v_pk_fma_f32 v[98:99], v[98:99], v[138:139], v[206:207]
	v_pk_fma_f32 v[96:97], v[96:97], v[136:137], v[204:205]
	global_store_dwordx4 v[188:189], v[108:111], off nt
	global_store_dwordx4 v[188:189], v[104:107], off offset:16 nt
	global_store_dwordx4 v[188:189], v[100:103], off offset:512 nt
	global_store_dwordx4 v[188:189], v[96:99], off offset:528 nt
	s_mov_b32 s98, 0x20000
	v_lshl_add_u64 v[188:189], v[188:189], 0, s[98:99]
	global_load_dwordx4 v[192:195], v[160:161], off nt
	global_load_dwordx4 v[196:199], v[160:161], off offset:16 nt
	global_load_dwordx4 v[200:203], v[160:161], off offset:512 nt
	global_load_dwordx4 v[204:207], v[160:161], off offset:528 nt
	s_mov_b32 s98, 0xa0000
	v_lshl_add_u64 v[160:161], v[160:161], 0, s[98:99]
	s_waitcnt vmcnt(8)
	v_pk_fma_f32 v[94:95], v[94:95], v[134:135], v[170:171]
	v_pk_fma_f32 v[92:93], v[92:93], v[132:133], v[168:169]
	v_pk_fma_f32 v[90:91], v[90:91], v[130:131], v[174:175]
	v_pk_fma_f32 v[88:89], v[88:89], v[128:129], v[172:173]
	v_pk_fma_f32 v[86:87], v[86:87], v[142:143], v[178:179]
	v_pk_fma_f32 v[84:85], v[84:85], v[140:141], v[176:177]
	v_pk_fma_f32 v[82:83], v[82:83], v[138:139], v[182:183]
	v_pk_fma_f32 v[80:81], v[80:81], v[136:137], v[180:181]
	global_store_dwordx4 v[188:189], v[92:95], off nt
	global_store_dwordx4 v[188:189], v[88:91], off offset:16 nt
	global_store_dwordx4 v[188:189], v[84:87], off offset:512 nt
	global_store_dwordx4 v[188:189], v[80:83], off offset:528 nt
	s_mov_b32 s98, 0x20000
	v_lshl_add_u64 v[188:189], v[188:189], 0, s[98:99]
	global_load_dwordx4 v[168:171], v[160:161], off nt
	global_load_dwordx4 v[172:175], v[160:161], off offset:16 nt
	global_load_dwordx4 v[176:179], v[160:161], off offset:512 nt
	global_load_dwordx4 v[180:183], v[160:161], off offset:528 nt
	s_mov_b32 s98, 0x20000
	v_lshl_add_u64 v[160:161], v[160:161], 0, s[98:99]
	s_waitcnt vmcnt(8)
; #define EPI_FENCE() asm volatile("" ::: "memory")
;     __device__ __forceinline__ void operator()(const Acc& acc, const Unit& u, int wr, int wc, int fr, int fq) const {
;     ...
;             for (int m = 0; m < 4; ++m) { const size_t off = (size_t)(row0 + ai * HALF + m * 16) * DM + col0;
; #pragma unroll
;                 for (int bj = 0; bj < 2; ++bj) {
;                     const f32x4 b0 = *(const f32x4*)(base + off + bj * HALF), b1 = *(const f32x4*)(base + off + bj * HALF + 4);
;                     *(f32x4*)(out + off + bj * HALF) = b0 + gv[bj][0] * acc[ai][bj][m][0];
;                     *(f32x4*)(out + off + bj * HALF + 4) = b1 + gv[bj][1] * acc[ai][bj][m][1]; }
;                 EPI_FENCE(); }
	v_pk_fma_f32 v[78:79], v[78:79], v[134:135], v[194:195]
	v_pk_fma_f32 v[76:77], v[76:77], v[132:133], v[192:193]
	v_pk_fma_f32 v[74:75], v[74:75], v[130:131], v[198:199]
	v_pk_fma_f32 v[72:73], v[72:73], v[128:129], v[196:197]
	v_pk_fma_f32 v[70:71], v[70:71], v[142:143], v[202:203]
	v_pk_fma_f32 v[68:69], v[68:69], v[140:141], v[200:201]
	v_pk_fma_f32 v[66:67], v[66:67], v[138:139], v[206:207]
	v_pk_fma_f32 v[64:65], v[64:65], v[136:137], v[204:205]
	global_store_dwordx4 v[188:189], v[76:79], off nt
	global_store_dwordx4 v[188:189], v[72:75], off offset:16 nt
	global_store_dwordx4 v[188:189], v[68:71], off offset:512 nt
	global_store_dwordx4 v[188:189], v[64:67], off offset:528 nt
	s_mov_b32 s98, 0xa0000
	v_lshl_add_u64 v[188:189], v[188:189], 0, s[98:99]
	global_load_dwordx4 v[192:195], v[160:161], off nt
	global_load_dwordx4 v[196:199], v[160:161], off offset:16 nt
	global_load_dwordx4 v[200:203], v[160:161], off offset:512 nt
	global_load_dwordx4 v[204:207], v[160:161], off offset:528 nt
	s_mov_b32 s98, 0x20000
	v_lshl_add_u64 v[160:161], v[160:161], 0, s[98:99]
	s_waitcnt vmcnt(8)
	v_pk_fma_f32 v[62:63], v[62:63], v[134:135], v[170:171]
	v_pk_fma_f32 v[60:61], v[60:61], v[132:133], v[168:169]
	v_pk_fma_f32 v[58:59], v[58:59], v[130:131], v[174:175]
	v_pk_fma_f32 v[56:57], v[56:57], v[128:129], v[172:173]
	v_pk_fma_f32 v[54:55], v[54:55], v[142:143], v[178:179]
	v_pk_fma_f32 v[52:53], v[52:53], v[140:141], v[176:177]
	v_pk_fma_f32 v[50:51], v[50:51], v[138:139], v[182:183]
	v_pk_fma_f32 v[48:49], v[48:49], v[136:137], v[180:181]
	global_store_dwordx4 v[188:189], v[60:63], off nt
	global_store_dwordx4 v[188:189], v[56:59], off offset:16 nt
	global_store_dwordx4 v[188:189], v[52:55], off offset:512 nt
	global_store_dwordx4 v[188:189], v[48:51], off offset:528 nt
	s_mov_b32 s98, 0x20000
	v_lshl_add_u64 v[188:189], v[188:189], 0, s[98:99]
	global_load_dwordx4 v[168:171], v[160:161], off nt
	global_load_dwordx4 v[172:175], v[160:161], off offset:16 nt
	global_load_dwordx4 v[176:179], v[160:161], off offset:512 nt
	global_load_dwordx4 v[180:183], v[160:161], off offset:528 nt
	s_mov_b32 s98, 0x20000
	v_lshl_add_u64 v[160:161], v[160:161], 0, s[98:99]
	s_waitcnt vmcnt(8)
	v_pk_fma_f32 v[46:47], v[46:47], v[134:135], v[194:195]
	v_pk_fma_f32 v[44:45], v[44:45], v[132:133], v[192:193]
	v_pk_fma_f32 v[42:43], v[42:43], v[130:131], v[198:199]
	v_pk_fma_f32 v[40:41], v[40:41], v[128:129], v[196:197]
	v_pk_fma_f32 v[38:39], v[38:39], v[142:143], v[202:203]
	v_pk_fma_f32 v[36:37], v[36:37], v[140:141], v[200:201]
	v_pk_fma_f32 v[34:35], v[34:35], v[138:139], v[206:207]
	v_pk_fma_f32 v[32:33], v[32:33], v[136:137], v[204:205]
	global_store_dwordx4 v[188:189], v[44:47], off nt
	global_store_dwordx4 v[188:189], v[40:43], off offset:16 nt
	global_store_dwordx4 v[188:189], v[36:39], off offset:512 nt
	global_store_dwordx4 v[188:189], v[32:35], off offset:528 nt
	s_mov_b32 s98, 0x20000
	v_lshl_add_u64 v[188:189], v[188:189], 0, s[98:99]
	global_load_dwordx4 v[192:195], v[160:161], off nt
	global_load_dwordx4 v[196:199], v[160:161], off offset:16 nt
	global_load_dwordx4 v[200:203], v[160:161], off offset:512 nt
	global_load_dwordx4 v[204:207], v[160:161], off offset:528 nt
	s_waitcnt vmcnt(8)
	v_pk_fma_f32 v[30:31], v[30:31], v[134:135], v[170:171]
	v_pk_fma_f32 v[28:29], v[28:29], v[132:133], v[168:169]
	v_pk_fma_f32 v[26:27], v[26:27], v[130:131], v[174:175]
	v_pk_fma_f32 v[24:25], v[24:25], v[128:129], v[172:173]
	v_pk_fma_f32 v[22:23], v[22:23], v[142:143], v[178:179]
	v_pk_fma_f32 v[20:21], v[20:21], v[140:141], v[176:177]
	v_pk_fma_f32 v[18:19], v[18:19], v[138:139], v[182:183]
	v_pk_fma_f32 v[16:17], v[16:17], v[136:137], v[180:181]
	global_store_dwordx4 v[188:189], v[28:31], off nt
	global_store_dwordx4 v[188:189], v[24:27], off offset:16 nt
	global_store_dwordx4 v[188:189], v[20:23], off offset:512 nt
	global_store_dwordx4 v[188:189], v[16:19], off offset:528 nt
	s_mov_b32 s98, 0x20000
	v_lshl_add_u64 v[188:189], v[188:189], 0, s[98:99]
	s_waitcnt vmcnt(4)
	v_pk_fma_f32 v[14:15], v[14:15], v[134:135], v[194:195]
	v_pk_fma_f32 v[12:13], v[12:13], v[132:133], v[192:193]
	v_pk_fma_f32 v[10:11], v[10:11], v[130:131], v[198:199]
	v_pk_fma_f32 v[8:9], v[8:9], v[128:129], v[196:197]
	v_pk_fma_f32 v[6:7], v[6:7], v[142:143], v[202:203]
	v_pk_fma_f32 v[4:5], v[4:5], v[140:141], v[200:201]
	v_pk_fma_f32 v[2:3], v[2:3], v[138:139], v[206:207]
	v_pk_fma_f32 v[0:1], v[0:1], v[136:137], v[204:205]
	global_store_dwordx4 v[188:189], v[12:15], off nt
	global_store_dwordx4 v[188:189], v[8:11], off offset:16 nt
	global_store_dwordx4 v[188:189], v[4:7], off offset:512 nt
	global_store_dwordx4 v[188:189], v[0:3], off offset:528 nt
	s_and_b64 vcc, exec, s[0:1]
	s_mov_b64 s[0:1], -1
	s_cbranch_vccnz .LBB0_1036
	s_andn2_b64 vcc, exec, s[6:7]
	s_cbranch_vccnz .LBB0_1035
	s_barrier
	s_branch .LBB0_1035
